# FFN-down epilogue: counted vmcnt ladder instead of one vmcnt(0) (stores start under the residual loads)
# baseline (speedup 1.0000x reference)
; __device__ __forceinline__ int lane_id() { int l; asm volatile("v_mbcnt_lo_u32_b32 %0, -1, 0\n\tv_mbcnt_hi_u32_b32 %0, -1, %0" : "=v"(l)); return l; }
; #define EPI_WVEC_LOOP _Pragma("unroll") for (int m2 = 0; m2 < 2; ++m2) _Pragma("unroll") for (int bj = 0; bj < 2; ++bj)
;     __device__ __forceinline__ void operator()(const f32x4 (&acc)[2][2][4][2], const pg8::Unit& u, int wr, int wc, int fr, int fq) const {
;         { const int l_ = lane_id(); fr = l_ & 15; fq = l_ >> 4; }
;         const float* mod = (const float*)(ws + WS_MOD); const int bb = (u.pm * 256) / SEQ; const float* g2 = mod + (size_t)bb * IN_COLS + 5 * D_MODEL; const bf16* XM = (const bf16*)(ws + WS_XM16);
;         f32x4 cg[2][2];
; #pragma unroll
;         for (int bj = 0; bj < 2; ++bj)
; #pragma unroll
;             for (int n = 0; n < 2; ++n) cg[bj][n] = *(const f32x4*)(g2 + u.pn * 256 + bj * 128 + wc * 32 + fq * 8 + 4 * n);
;         u32x4 xv[4][4];
; #pragma unroll
;         for (int b = 0; b < 4; ++b) { EPI_PIPE_IDX(b); EPI_WVEC_LOOP { EPI_WVEC_IDX; xv[b][wi] = *(const u32x4*)((const char*)XM + off * 2u); } }
; #pragma unroll
;         for (int b = 0; b < 4; ++b) { EPI_PIPE_IDX(b);
;             EPI_WVEC_LOOP { EPI_WVEC_IDX; const u32x4 xw = xv[b][wi];
;                 const f32x4 x0 = (f32x4){bflo(xw.x), bfhi(xw.x), bflo(xw.y), bfhi(xw.y)}, x1 = (f32x4){bflo(xw.z), bfhi(xw.z), bflo(xw.w), bfhi(xw.w)};
;                 *(f32x4*)((char*)out + off * 4u) = x0 + cg[bj][0] * acc[ai][bj][m][0]; *(f32x4*)((char*)out + off * 4u + 16) = x1 + cg[bj][1] * acc[ai][bj][m][1]; }
;         }
;     }
.LBB0_1025:
	s_ashr_i32 s22, s51, 31
	s_lshr_b32 s22, s22, 29
	s_add_i32 s22, s51, s22
	s_ashr_i32 s22, s22, 3
	s_mul_hi_i32 s23, s22, 0xc000
	s_mul_i32 s22, s22, 0xc000
	s_add_u32 s24, s14, s22
	s_addc_u32 s25, s15, s23
	s_lshl_b32 s22, s52, 8
	s_ashr_i32 s23, s22, 31
	s_lshl_b64 s[22:23], s[22:23], 2
	s_add_u32 s22, s24, s22
	s_addc_u32 s23, s25, s23
	s_add_u32 s22, s22, s47
	s_addc_u32 s23, s23, 0
	s_lshl_b32 s24, s51, 8
	s_add_i32 s24, s24, s40
	v_mbcnt_lo_u32_b32 v128, -1, 0
	v_mbcnt_hi_u32_b32 v128, -1, v128
	s_nop 0
	v_and_or_b32 v145, v128, 15, s24
	s_lshl_b32 s24, s52, 9
	v_ashrrev_i32_e32 v144, 4, v128
	v_and_b32_e32 v128, -16, v128
	s_or_b32 s24, s24, s43
	v_add_u32_e32 v128, s24, v128
	v_lshl_add_u32 v146, v145, 12, v128
	v_lshlrev_b32_e32 v128, 3, v144
	v_ashrrev_i32_e32 v129, 31, v128
	v_lshl_add_u64 v[128:129], v[128:129], 2, s[22:23]
	v_add_co_u32_e32 v130, vcc, s48, v128
	global_load_dwordx4 v[206:209], v146, s[16:17]
	s_nop 0
	v_addc_co_u32_e32 v131, vcc, 0, v129, vcc
	v_lshl_add_u64 v[128:129], v[128:129], 0, s[18:19]
	global_load_dwordx4 v[140:143], v[130:131], off
	global_load_dwordx4 v[136:139], v[128:129], off offset:16
	v_add_u32_e32 v130, 0x100, v146
	global_load_dwordx4 v[210:213], v130, s[16:17]
	global_load_dwordx4 v[132:135], v[128:129], off offset:512
	s_nop 0
	global_load_dwordx4 v[128:131], v[128:129], off offset:528
	v_add_u32_e32 v147, 0x10000, v146
	global_load_dwordx4 v[214:217], v147, s[16:17]
	v_add_u32_e32 v147, 0x10100, v146
	global_load_dwordx4 v[218:221], v147, s[16:17]
	v_add_u32_e32 v147, 0x20000, v146
	global_load_dwordx4 v[222:225], v147, s[16:17]
	s_lshl_b32 s22, s52, 10
	v_lshlrev_b32_e32 v144, 5, v144
	s_or_b32 s22, s22, s44
	v_lshlrev_b32_e32 v145, 13, v145
	v_add_u32_e32 v148, 0x20100, v146
	v_add_u32_e32 v149, 0x30000, v146
	v_add_u32_e32 v150, 0x30100, v146
	v_add_u32_e32 v151, 0x80000, v146
	v_add_u32_e32 v147, 0x80100, v146
	v_add_u32_e32 v152, 0x90000, v146
	v_add_u32_e32 v153, 0x90100, v146
	v_add_u32_e32 v154, 0xa0000, v146
	v_add_u32_e32 v155, 0xa0100, v146
	v_add_u32_e32 v205, 0xb0000, v146
	v_add_u32_e32 v146, 0xb0100, v146
	v_add3_u32 v204, s22, v144, v145
	global_load_dwordx4 v[226:229], v148, s[16:17]
	global_load_dwordx4 v[180:183], v149, s[16:17]
	global_load_dwordx4 v[176:179], v150, s[16:17]
	global_load_dwordx4 v[172:175], v151, s[16:17]
	global_load_dwordx4 v[168:171], v147, s[16:17]
	global_load_dwordx4 v[164:167], v152, s[16:17]
	global_load_dwordx4 v[160:163], v153, s[16:17]
	global_load_dwordx4 v[156:159], v154, s[16:17]
	s_nop 0
	global_load_dwordx4 v[152:155], v155, s[16:17]
	s_nop 0
	global_load_dwordx4 v[148:151], v205, s[16:17]
	s_nop 0
	global_load_dwordx4 v[144:147], v146, s[16:17]
	v_add_u32_e32 v205, 0x200, v204
	s_and_b64 vcc, exec, s[0:1]
	s_mov_b64 s[0:1], -1
	s_waitcnt vmcnt(14)
	v_lshlrev_b32_e32 v230, 16, v206
	v_and_b32_e32 v231, 0xffff0000, v206
	v_lshlrev_b32_e32 v206, 16, v207
	v_and_b32_e32 v207, 0xffff0000, v207
	v_lshlrev_b32_e32 v232, 16, v208
	v_and_b32_e32 v233, 0xffff0000, v208
	v_lshlrev_b32_e32 v208, 16, v209
	v_and_b32_e32 v209, 0xffff0000, v209
	v_pk_fma_f32 v[126:127], v[126:127], v[142:143], v[206:207]
	v_pk_fma_f32 v[122:123], v[122:123], v[138:139], v[208:209]
	v_lshlrev_b32_e32 v206, 16, v210
	v_and_b32_e32 v207, 0xffff0000, v210
	v_lshlrev_b32_e32 v208, 16, v211
	v_and_b32_e32 v209, 0xffff0000, v211
	v_lshlrev_b32_e32 v210, 16, v212
	v_and_b32_e32 v211, 0xffff0000, v212
	v_lshlrev_b32_e32 v212, 16, v213
	v_and_b32_e32 v213, 0xffff0000, v213
	v_pk_fma_f32 v[124:125], v[124:125], v[140:141], v[230:231]
	v_pk_fma_f32 v[116:117], v[116:117], v[132:133], v[206:207]
	v_pk_fma_f32 v[118:119], v[118:119], v[134:135], v[208:209]
	v_pk_fma_f32 v[108:109], v[108:109], v[128:129], v[210:211]
	v_pk_fma_f32 v[110:111], v[110:111], v[130:131], v[212:213]
	v_pk_fma_f32 v[120:121], v[120:121], v[136:137], v[232:233]
	global_store_dwordx4 v204, v[124:127], s[12:13]
	global_store_dwordx4 v204, v[120:123], s[12:13] offset:16
	global_store_dwordx4 v205, v[116:119], s[12:13]
	global_store_dwordx4 v205, v[108:111], s[12:13] offset:16
	s_waitcnt vmcnt(17)
	v_add_u32_e32 v120, 0x20000, v204
	v_lshlrev_b32_e32 v116, 16, v216
	v_lshlrev_b32_e32 v108, 16, v214
	v_and_b32_e32 v109, 0xffff0000, v214
	v_lshlrev_b32_e32 v110, 16, v215
	v_and_b32_e32 v111, 0xffff0000, v215
	v_and_b32_e32 v117, 0xffff0000, v216
	v_lshlrev_b32_e32 v118, 16, v217
	v_and_b32_e32 v119, 0xffff0000, v217
	v_pk_fma_f32 v[110:111], v[114:115], v[142:143], v[110:111]
	v_pk_fma_f32 v[108:109], v[112:113], v[140:141], v[108:109]
	v_pk_fma_f32 v[104:105], v[104:105], v[136:137], v[116:117]
	v_pk_fma_f32 v[106:107], v[106:107], v[138:139], v[118:119]
	global_store_dwordx4 v120, v[108:111], s[12:13]
	global_store_dwordx4 v120, v[104:107], s[12:13] offset:16
	s_waitcnt vmcnt(18)
	s_nop 0
	v_lshlrev_b32_e32 v108, 16, v220
	v_lshlrev_b32_e32 v104, 16, v218
	v_and_b32_e32 v105, 0xffff0000, v218
	v_lshlrev_b32_e32 v106, 16, v219
	v_and_b32_e32 v107, 0xffff0000, v219
	v_and_b32_e32 v109, 0xffff0000, v220
	v_lshlrev_b32_e32 v110, 16, v221
	v_and_b32_e32 v111, 0xffff0000, v221
	v_pk_fma_f32 v[100:101], v[100:101], v[132:133], v[104:105]
	v_pk_fma_f32 v[102:103], v[102:103], v[134:135], v[106:107]
	v_add_u32_e32 v104, 0x20200, v204
	v_pk_fma_f32 v[92:93], v[92:93], v[128:129], v[108:109]
	v_pk_fma_f32 v[94:95], v[94:95], v[130:131], v[110:111]
	global_store_dwordx4 v104, v[100:103], s[12:13]
	global_store_dwordx4 v104, v[92:95], s[12:13] offset:16
	s_waitcnt vmcnt(19)
; #define EPI_WVEC_LOOP _Pragma("unroll") for (int m2 = 0; m2 < 2; ++m2) _Pragma("unroll") for (int bj = 0; bj < 2; ++bj)
;     __device__ __forceinline__ void operator()(const f32x4 (&acc)[2][2][4][2], const pg8::Unit& u, int wr, int wc, int fr, int fq) const {
;     ...
;         for (int b = 0; b < 4; ++b) { EPI_PIPE_IDX(b);
;             EPI_WVEC_LOOP { EPI_WVEC_IDX; const u32x4 xw = xv[b][wi];
;                 const f32x4 x0 = (f32x4){bflo(xw.x), bfhi(xw.x), bflo(xw.y), bfhi(xw.y)}, x1 = (f32x4){bflo(xw.z), bfhi(xw.z), bflo(xw.w), bfhi(xw.w)};
;                 *(f32x4*)((char*)out + off * 4u) = x0 + cg[bj][0] * acc[ai][bj][m][0]; *(f32x4*)((char*)out + off * 4u + 16) = x1 + cg[bj][1] * acc[ai][bj][m][1]; }
;         }
	v_add_u32_e32 v104, 0x40000, v204
	v_lshlrev_b32_e32 v100, 16, v224
	v_lshlrev_b32_e32 v92, 16, v222
	v_and_b32_e32 v93, 0xffff0000, v222
	v_lshlrev_b32_e32 v94, 16, v223
	v_and_b32_e32 v95, 0xffff0000, v223
	v_and_b32_e32 v101, 0xffff0000, v224
	v_lshlrev_b32_e32 v102, 16, v225
	v_and_b32_e32 v103, 0xffff0000, v225
	v_pk_fma_f32 v[94:95], v[98:99], v[142:143], v[94:95]
	v_pk_fma_f32 v[92:93], v[96:97], v[140:141], v[92:93]
	v_pk_fma_f32 v[88:89], v[88:89], v[136:137], v[100:101]
	v_pk_fma_f32 v[90:91], v[90:91], v[138:139], v[102:103]
	global_store_dwordx4 v104, v[92:95], s[12:13]
	global_store_dwordx4 v104, v[88:91], s[12:13] offset:16
	s_waitcnt vmcnt(20)
	s_nop 0
	v_lshlrev_b32_e32 v92, 16, v228
	v_lshlrev_b32_e32 v88, 16, v226
	v_and_b32_e32 v89, 0xffff0000, v226
	v_lshlrev_b32_e32 v90, 16, v227
	v_and_b32_e32 v91, 0xffff0000, v227
	v_and_b32_e32 v93, 0xffff0000, v228
	v_lshlrev_b32_e32 v94, 16, v229
	v_and_b32_e32 v95, 0xffff0000, v229
	v_pk_fma_f32 v[84:85], v[84:85], v[132:133], v[88:89]
	v_pk_fma_f32 v[86:87], v[86:87], v[134:135], v[90:91]
	v_add_u32_e32 v88, 0x40200, v204
	v_pk_fma_f32 v[76:77], v[76:77], v[128:129], v[92:93]
	v_pk_fma_f32 v[78:79], v[78:79], v[130:131], v[94:95]
	global_store_dwordx4 v88, v[84:87], s[12:13]
	global_store_dwordx4 v88, v[76:79], s[12:13] offset:16
	s_waitcnt vmcnt(21)
	v_add_u32_e32 v88, 0x60000, v204
	v_lshlrev_b32_e32 v84, 16, v182
	v_lshlrev_b32_e32 v76, 16, v180
	v_and_b32_e32 v77, 0xffff0000, v180
	v_lshlrev_b32_e32 v78, 16, v181
	v_and_b32_e32 v79, 0xffff0000, v181
	v_and_b32_e32 v85, 0xffff0000, v182
	v_lshlrev_b32_e32 v86, 16, v183
	v_and_b32_e32 v87, 0xffff0000, v183
	v_pk_fma_f32 v[78:79], v[82:83], v[142:143], v[78:79]
	v_pk_fma_f32 v[76:77], v[80:81], v[140:141], v[76:77]
	v_pk_fma_f32 v[72:73], v[72:73], v[136:137], v[84:85]
	v_pk_fma_f32 v[74:75], v[74:75], v[138:139], v[86:87]
	global_store_dwordx4 v88, v[76:79], s[12:13]
	global_store_dwordx4 v88, v[72:75], s[12:13] offset:16
	s_waitcnt vmcnt(22)
	s_nop 0
	v_lshlrev_b32_e32 v76, 16, v178
	v_lshlrev_b32_e32 v72, 16, v176
	v_and_b32_e32 v73, 0xffff0000, v176
	v_lshlrev_b32_e32 v74, 16, v177
	v_and_b32_e32 v75, 0xffff0000, v177
	v_and_b32_e32 v77, 0xffff0000, v178
	v_lshlrev_b32_e32 v78, 16, v179
	v_and_b32_e32 v79, 0xffff0000, v179
	v_pk_fma_f32 v[68:69], v[68:69], v[132:133], v[72:73]
	v_pk_fma_f32 v[70:71], v[70:71], v[134:135], v[74:75]
	v_add_u32_e32 v72, 0x60200, v204
	v_pk_fma_f32 v[64:65], v[64:65], v[128:129], v[76:77]
	v_pk_fma_f32 v[66:67], v[66:67], v[130:131], v[78:79]
	global_store_dwordx4 v72, v[68:71], s[12:13]
	global_store_dwordx4 v72, v[64:67], s[12:13] offset:16
	s_waitcnt vmcnt(23)
	v_add_u32_e32 v72, 0x100000, v204
	v_lshlrev_b32_e32 v68, 16, v174
	v_lshlrev_b32_e32 v64, 16, v172
	v_and_b32_e32 v65, 0xffff0000, v172
	v_lshlrev_b32_e32 v66, 16, v173
	v_and_b32_e32 v67, 0xffff0000, v173
	v_and_b32_e32 v69, 0xffff0000, v174
	v_lshlrev_b32_e32 v70, 16, v175
	v_and_b32_e32 v71, 0xffff0000, v175
	v_pk_fma_f32 v[62:63], v[62:63], v[142:143], v[66:67]
	v_pk_fma_f32 v[60:61], v[60:61], v[140:141], v[64:65]
	v_pk_fma_f32 v[56:57], v[56:57], v[136:137], v[68:69]
	v_pk_fma_f32 v[58:59], v[58:59], v[138:139], v[70:71]
	global_store_dwordx4 v72, v[60:63], s[12:13]
	global_store_dwordx4 v72, v[56:59], s[12:13] offset:16
	s_waitcnt vmcnt(24)
	s_nop 0
	v_lshlrev_b32_e32 v60, 16, v170
	v_lshlrev_b32_e32 v56, 16, v168
	v_and_b32_e32 v57, 0xffff0000, v168
	v_lshlrev_b32_e32 v58, 16, v169
	v_and_b32_e32 v59, 0xffff0000, v169
	v_and_b32_e32 v61, 0xffff0000, v170
	v_lshlrev_b32_e32 v62, 16, v171
	v_and_b32_e32 v63, 0xffff0000, v171
	v_pk_fma_f32 v[52:53], v[52:53], v[132:133], v[56:57]
	v_pk_fma_f32 v[54:55], v[54:55], v[134:135], v[58:59]
	v_add_u32_e32 v56, 0x100200, v204
	v_pk_fma_f32 v[44:45], v[44:45], v[128:129], v[60:61]
	v_pk_fma_f32 v[46:47], v[46:47], v[130:131], v[62:63]
	global_store_dwordx4 v56, v[52:55], s[12:13]
	global_store_dwordx4 v56, v[44:47], s[12:13] offset:16
	s_waitcnt vmcnt(25)
; #define EPI_WVEC_LOOP _Pragma("unroll") for (int m2 = 0; m2 < 2; ++m2) _Pragma("unroll") for (int bj = 0; bj < 2; ++bj)
;     __device__ __forceinline__ void operator()(const f32x4 (&acc)[2][2][4][2], const pg8::Unit& u, int wr, int wc, int fr, int fq) const {
;     ...
;         for (int b = 0; b < 4; ++b) { EPI_PIPE_IDX(b);
;             EPI_WVEC_LOOP { EPI_WVEC_IDX; const u32x4 xw = xv[b][wi];
;                 const f32x4 x0 = (f32x4){bflo(xw.x), bfhi(xw.x), bflo(xw.y), bfhi(xw.y)}, x1 = (f32x4){bflo(xw.z), bfhi(xw.z), bflo(xw.w), bfhi(xw.w)};
;                 *(f32x4*)((char*)out + off * 4u) = x0 + cg[bj][0] * acc[ai][bj][m][0]; *(f32x4*)((char*)out + off * 4u + 16) = x1 + cg[bj][1] * acc[ai][bj][m][1]; }
;         }
	v_add_u32_e32 v56, 0x120000, v204
	v_lshlrev_b32_e32 v52, 16, v166
	v_lshlrev_b32_e32 v44, 16, v164
	v_and_b32_e32 v45, 0xffff0000, v164
	v_lshlrev_b32_e32 v46, 16, v165
	v_and_b32_e32 v47, 0xffff0000, v165
	v_and_b32_e32 v53, 0xffff0000, v166
	v_lshlrev_b32_e32 v54, 16, v167
	v_and_b32_e32 v55, 0xffff0000, v167
	v_pk_fma_f32 v[46:47], v[50:51], v[142:143], v[46:47]
	v_pk_fma_f32 v[44:45], v[48:49], v[140:141], v[44:45]
	v_pk_fma_f32 v[40:41], v[40:41], v[136:137], v[52:53]
	v_pk_fma_f32 v[42:43], v[42:43], v[138:139], v[54:55]
	global_store_dwordx4 v56, v[44:47], s[12:13]
	global_store_dwordx4 v56, v[40:43], s[12:13] offset:16
	s_waitcnt vmcnt(26)
	s_nop 0
	v_lshlrev_b32_e32 v44, 16, v162
	v_lshlrev_b32_e32 v40, 16, v160
	v_and_b32_e32 v41, 0xffff0000, v160
	v_lshlrev_b32_e32 v42, 16, v161
	v_and_b32_e32 v43, 0xffff0000, v161
	v_and_b32_e32 v45, 0xffff0000, v162
	v_lshlrev_b32_e32 v46, 16, v163
	v_and_b32_e32 v47, 0xffff0000, v163
	v_pk_fma_f32 v[36:37], v[36:37], v[132:133], v[40:41]
	v_pk_fma_f32 v[38:39], v[38:39], v[134:135], v[42:43]
	v_add_u32_e32 v40, 0x120200, v204
	v_pk_fma_f32 v[28:29], v[28:29], v[128:129], v[44:45]
	v_pk_fma_f32 v[30:31], v[30:31], v[130:131], v[46:47]
	global_store_dwordx4 v40, v[36:39], s[12:13]
	global_store_dwordx4 v40, v[28:31], s[12:13] offset:16
	s_waitcnt vmcnt(27)
	v_add_u32_e32 v40, 0x140000, v204
	v_lshlrev_b32_e32 v36, 16, v158
	v_lshlrev_b32_e32 v28, 16, v156
	v_and_b32_e32 v29, 0xffff0000, v156
	v_lshlrev_b32_e32 v30, 16, v157
	v_and_b32_e32 v31, 0xffff0000, v157
	v_and_b32_e32 v37, 0xffff0000, v158
	v_lshlrev_b32_e32 v38, 16, v159
	v_and_b32_e32 v39, 0xffff0000, v159
	v_pk_fma_f32 v[30:31], v[34:35], v[142:143], v[30:31]
	v_pk_fma_f32 v[28:29], v[32:33], v[140:141], v[28:29]
	v_pk_fma_f32 v[24:25], v[24:25], v[136:137], v[36:37]
	v_pk_fma_f32 v[26:27], v[26:27], v[138:139], v[38:39]
	global_store_dwordx4 v40, v[28:31], s[12:13]
	global_store_dwordx4 v40, v[24:27], s[12:13] offset:16
	s_waitcnt vmcnt(28)
	s_nop 0
	v_lshlrev_b32_e32 v28, 16, v154
	v_lshlrev_b32_e32 v24, 16, v152
	v_and_b32_e32 v25, 0xffff0000, v152
	v_lshlrev_b32_e32 v26, 16, v153
	v_and_b32_e32 v27, 0xffff0000, v153
	v_and_b32_e32 v29, 0xffff0000, v154
	v_lshlrev_b32_e32 v30, 16, v155
	v_and_b32_e32 v31, 0xffff0000, v155
	v_pk_fma_f32 v[20:21], v[20:21], v[132:133], v[24:25]
	v_pk_fma_f32 v[22:23], v[22:23], v[134:135], v[26:27]
	v_add_u32_e32 v24, 0x140200, v204
	v_pk_fma_f32 v[12:13], v[12:13], v[128:129], v[28:29]
	v_pk_fma_f32 v[14:15], v[14:15], v[130:131], v[30:31]
	global_store_dwordx4 v24, v[20:23], s[12:13]
	global_store_dwordx4 v24, v[12:15], s[12:13] offset:16
	s_waitcnt vmcnt(29)
	v_add_u32_e32 v24, 0x160000, v204
	v_lshlrev_b32_e32 v20, 16, v150
	v_lshlrev_b32_e32 v12, 16, v148
	v_and_b32_e32 v13, 0xffff0000, v148
	v_lshlrev_b32_e32 v14, 16, v149
	v_and_b32_e32 v15, 0xffff0000, v149
	v_and_b32_e32 v21, 0xffff0000, v150
	v_lshlrev_b32_e32 v22, 16, v151
	v_and_b32_e32 v23, 0xffff0000, v151
	v_pk_fma_f32 v[14:15], v[18:19], v[142:143], v[14:15]
	v_pk_fma_f32 v[12:13], v[16:17], v[140:141], v[12:13]
	v_pk_fma_f32 v[8:9], v[8:9], v[136:137], v[20:21]
	v_pk_fma_f32 v[10:11], v[10:11], v[138:139], v[22:23]
	global_store_dwordx4 v24, v[12:15], s[12:13]
	global_store_dwordx4 v24, v[8:11], s[12:13] offset:16
	s_waitcnt vmcnt(30)
	s_nop 0
	v_lshlrev_b32_e32 v12, 16, v146
	v_lshlrev_b32_e32 v8, 16, v144
	v_and_b32_e32 v9, 0xffff0000, v144
	v_lshlrev_b32_e32 v10, 16, v145
	v_and_b32_e32 v11, 0xffff0000, v145
	v_and_b32_e32 v13, 0xffff0000, v146
	v_lshlrev_b32_e32 v14, 16, v147
	v_and_b32_e32 v15, 0xffff0000, v147
	v_pk_fma_f32 v[4:5], v[4:5], v[132:133], v[8:9]
	v_pk_fma_f32 v[6:7], v[6:7], v[134:135], v[10:11]
	v_add_u32_e32 v8, 0x160200, v204
	v_pk_fma_f32 v[0:1], v[0:1], v[128:129], v[12:13]
	v_pk_fma_f32 v[2:3], v[2:3], v[130:131], v[14:15]
	global_store_dwordx4 v8, v[4:7], s[12:13]
	global_store_dwordx4 v8, v[0:3], s[12:13] offset:16
	s_cbranch_vccnz .LBB0_1010
	s_andn2_b64 vcc, exec, s[6:7]
	s_cbranch_vccnz .LBB0_1009
	s_barrier
	s_branch .LBB0_1009
